# attention: one static s_setprio 1 for the younger wave half (waves 4-7), reset at phase exit
# baseline (speedup 1.0000x reference)
; #define LAS __attribute__((address_space(3)))
; __device__ __forceinline__ int opaque_tid() { int t = threadIdx.x; asm volatile("" : "+v"(t)); return t; }
; __device__ __forceinline__ void ph_attn(const Params& p, LAS unsigned char* lds) {
;     const int tid = opaque_tid(), lane = tid & 63, w = __builtin_amdgcn_readfirstlane(tid >> 6), fr = lane & 15, fq = lane >> 4;
;     unsigned char* ws = p.ws; const bf16_t* qb = (const bf16_t*)(ws + WS_A); const bf16_t* kb = (const bf16_t*)(ws + WS_KB); const bf16_t* vt = (const bf16_t*)(ws + WS_VT); bf16_t* ao = (bf16_t*)(ws + WS_B);
;     constexpr int PR = 36864;
;     LAS unsigned char* pw = lds + PR + w * 8448 + fr * 528 + fq * 8;
;     const unsigned koff = (unsigned)((tid >> 5) * 1024 + (tid & 31) * 8);
;     const unsigned voff = (unsigned)((tid >> 3) * 256 + (tid & 7) * 8);
;     LAS unsigned char* kst = lds + (tid >> 5) * 528 + (tid & 31) * 16;
;     LAS unsigned char* vst = lds + (tid >> 3) * 144 + (tid & 7) * 16;
;     const LAS unsigned char* krd = lds + fr * 528 + fq * 16;
;     const LAS unsigned char* vrd = lds + fr * 144 + fq * 16;
; #pragma unroll 1
;     for (int u = blockIdx.x; u < 1088; u += gridDim.x) {
.LBB0_1080:
	s_cmp_lt_i32 s94, 9
	s_cselect_b64 s[0:1], -1, 0
	s_and_b64 s[4:5], s[0:1], s[4:5]
	s_andn2_b64 vcc, exec, s[4:5]
	s_cbranch_vccnz .LBB0_1110
	v_mov_b32_e32 v0, v200
	s_cmpk_gt_i32 s2, 0x43f
	s_nop 0
	v_readfirstlane_b32 s4, v0
	s_cbranch_scc1 .LBB0_1110
	s_add_u32 s6, s92, 0x11680000
	s_addc_u32 s7, s93, 0
	s_add_u32 s3, s92, 0x19c80000
	s_addc_u32 s14, s93, 0
	s_add_u32 s15, s92, 0x1a880000
	s_addc_u32 s20, s93, 0
	s_add_u32 s8, s92, 0x15780000
	s_addc_u32 s9, s93, 0
	s_ashr_i32 s4, s4, 6
	s_waitcnt lgkmcnt(0)
	v_and_b32_e32 v1, 15, v0
	s_waitcnt vmcnt(0)
	v_bfe_u32 v3, v0, 4, 2
	s_mul_i32 s5, s4, 0x2100
	v_ashrrev_i32_e32 v4, 5, v0
	v_and_b32_e32 v6, 31, v0
	v_ashrrev_i32_e32 v7, 3, v0
	v_and_b32_e32 v0, 7, v0
	s_add_i32 s10, s5, 0
	v_lshlrev_b32_e32 v11, 4, v0
	v_lshlrev_b32_e32 v0, 3, v0
	s_movk_i32 s12, 0x210
	v_mov_b32_e32 v2, s10
	s_movk_i32 s10, 0x90
	v_lshl_or_b32 v180, v7, 8, v0
	v_lshlrev_b32_e32 v0, 3, v6
	v_mad_u32_u24 v5, v1, s12, v2
	v_lshlrev_b32_e32 v2, 3, v3
	v_mul_lo_u32 v8, v4, s12
	v_mul_lo_u32 v10, v7, s10
	v_mad_u32_u24 v12, v1, s12, 0
	v_lshlrev_b32_e32 v13, 4, v3
	s_movk_i32 s10, 0xfe80
	v_lshl_or_b32 v182, v4, 10, v0
	s_lshl_b32 s21, s4, 4
	v_lshlrev_b32_e32 v4, 2, v3
	v_mov_b32_e32 v3, s5
	v_add_u32_e32 v193, v12, v13
	v_mad_i32_i24 v12, v1, s10, v12
	v_or_b32_e32 v196, s21, v1
	v_mad_u32_u24 v1, v1, s12, v3
	v_mov_b32_e32 v0, 0
	v_add3_u32 v1, v1, v13, 0
	v_add_u32_e32 v8, 0, v8
	v_lshlrev_b32_e32 v9, 4, v6
	v_add_u32_e32 v10, 0, v10
	v_mov_b32_e32 v181, v0
	v_add_u32_e32 v197, 0x9000, v1
	v_mbcnt_lo_u32_b32 v1, -1, 0
	s_mov_b32 s11, 0
	v_mov_b32_e32 v183, v0
	v_lshl_add_u64 v[184:185], v[180:181], 1, s[92:93]
	s_mov_b32 s22, 0x8000
	v_lshlrev_b32_e32 v186, 1, v2
	s_mov_b32 s23, 0x10000
	s_mov_b32 s24, 0x18000
	s_mov_b32 s25, 0x20000
	s_mov_b32 s26, 0xff61b1e6
	v_add_u32_e32 v198, v5, v2
	v_add_u32_e32 v199, v10, v11
	v_add_u32_e32 v201, v12, v13
	v_lshlrev_b32_e32 v188, 1, v4
	v_add_u32_e32 v202, v8, v9
	v_mbcnt_hi_u32_b32 v203, -1, v1
	s_mov_b32 s27, s2
	s_mov_b32 s96, 0
	v_lshrrev_b32_e32 v237, 3, v200
	v_and_b32_e32 v238, 7, v200
	v_bfe_u32 v239, v200, 4, 3
	v_xor_b32_e32 v238, v238, v239
	v_lshlrev_b32_e32 v238, 4, v238
	v_lshl_add_u32 v199, v237, 7, v238
	v_and_b32_e32 v237, 15, v200
	v_bfe_u32 v238, v200, 4, 2
	v_bfe_u32 v239, v200, 1, 3
	v_xor_b32_e32 v238, v238, v239
	v_lshlrev_b32_e32 v238, 4, v238
	v_lshl_add_u32 v201, v237, 7, v238
	v_xor_b32_e32 v239, 64, v201
	v_lshrrev_b32_e32 v237, 5, v200
	v_and_b32_e32 v238, 31, v200
	v_xor_b32_e32 v238, v238, v237
	v_lshlrev_b32_e32 v238, 4, v238
	v_lshl_add_u32 v202, v237, 9, v238
	v_and_b32_e32 v237, 15, v200
	v_bfe_u32 v238, v200, 4, 2
	v_and_b32_e32 v193, 3, v237
	v_xor_b32_e32 v238, v238, v193
	v_lshlrev_b32_e32 v238, 4, v238
	v_lshrrev_b32_e32 v193, 2, v237
	v_lshl_add_u32 v238, v193, 6, v238
	v_lshl_add_u32 v193, v237, 9, v238
	v_lshrrev_b32_e32 v237, 6, v200
	v_mul_u32_u24_e32 v237, 0x2100, v237
	v_bfe_u32 v238, v200, 5, 1
	v_mul_u32_u24_e32 v238, 0x210, v238
	v_and_b32_e32 v205, 31, v200
	v_lshlrev_b32_e32 v205, 4, v205
	v_add3_u32 v205, v205, v237, v238
	v_add_u32_e32 v205, 0x9000, v205
	v_and_b32_e32 v238, 15, v200
	v_mul_u32_u24_e32 v238, 0x210, v238
	v_bfe_u32 v206, v200, 4, 2
	v_lshlrev_b32_e32 v206, 3, v206
	v_add3_u32 v206, v206, v237, v238
	v_add_u32_e32 v206, 0x9000, v206
	v_readfirstlane_b32 s97, v200
	s_nop 3
	s_lshr_b32 s97, s97, 6
	s_cmp_ge_u32 s97, 4
	s_cbranch_scc0 .Lat_prio_done
	s_setprio 1
.Lat_prio_done:
	s_branch .LBB0_1084

; __device__ __forceinline__ unsigned xb_ld(unsigned* p)              { return __hip_atomic_load(p, __ATOMIC_RELAXED, __HIP_MEMORY_SCOPE_AGENT); }
; __device__ __forceinline__ void xcd_barrier_complete(unsigned* bar, unsigned x, unsigned& nloc, unsigned& nx) {
;     const unsigned G = gridDim.x * gridDim.y * gridDim.z;
;     unsigned sum, cnt, mine, sp = 0u;
;     for (;;) {
;         sum = 0u; cnt = 0u; mine = 0u;
; #pragma unroll
;         for (unsigned j = 0; j < 16; ++j) { const unsigned c = xb_ld(&bar[XB_XCNT(j)]); sum += c; cnt += (c > 0u) ? 1u : 0u; mine = (j == x) ? c : mine; }
; __device__ __forceinline__ void xcd_barrier(const XcdBarrier& b) {
;     asm volatile("s_waitcnt vmcnt(0)" ::: "memory");
;     __syncthreads();
;     if (threadIdx.x == 0) {
;         unsigned* bar = b.bar;
;         __builtin_amdgcn_s_waitcnt(0);
;         unsigned nloc = b.st[0], nx = b.st[1];
;         if (nloc == 0u) { xcd_barrier_complete(bar, b.x, nloc, nx); b.st[0] = nloc; b.st[1] = nx; }
.LBB0_1110:
	s_setprio 0
	s_cmp_gt_i32 s95, 9
	s_cselect_b64 s[4:5], -1, 0
	s_and_b64 s[0:1], s[0:1], s[4:5]
	s_andn2_b64 vcc, exec, s[0:1]
	s_cbranch_vccnz .LBB0_1164
	s_waitcnt vmcnt(0)
	s_waitcnt vmcnt(0) lgkmcnt(0)
	s_barrier
	s_and_saveexec_b64 s[0:1], s[72:73]
	s_cbranch_execz .LBB0_1163
	s_add_i32 s3, 0, 0x20000
	v_mov_b32_e32 v0, s3
	s_waitcnt vmcnt(0) expcnt(0) lgkmcnt(0)
	ds_read_b32 v2, v0
	s_add_i32 s3, 0, 0x20004
	v_mov_b32_e32 v0, s3
	ds_read_b32 v0, v0
	s_waitcnt lgkmcnt(1)
	v_cmp_ne_u32_e32 vcc, 0, v2
	s_cbranch_vccnz .LBB0_1127
	v_readlane_b32 s6, v236, 0
	v_readlane_b32 s7, v236, 1
	s_load_dwordx2 s[10:11], s[6:7], 0x4
	s_add_u32 s6, s92, 0x1db3ea00
	s_addc_u32 s7, s93, 0
	s_add_u32 s8, s92, 0x1db3ec00
	s_addc_u32 s9, s93, 0
	s_waitcnt lgkmcnt(0)
	s_mul_i32 s3, s10, s34
	s_add_u32 s10, s92, 0x1db3ed00
	s_mul_i32 s3, s3, s11
	s_addc_u32 s11, s93, 0
	s_add_u32 s12, s92, 0x1db3ee00
	s_addc_u32 s13, s93, 0
	s_add_u32 s16, s92, 0x1db3ef00
	s_addc_u32 s17, s93, 0
	s_add_u32 s18, s92, 0x1db3f000
	s_addc_u32 s19, s93, 0
	s_add_u32 s20, s92, 0x1db3f100
	s_addc_u32 s21, s93, 0
	s_add_u32 s22, s92, 0x1db3f200
	s_addc_u32 s23, s93, 0
	s_add_u32 s24, s92, 0x1db3f300
	s_addc_u32 s25, s93, 0
	s_add_u32 s26, s92, 0x1db3f400
	s_addc_u32 s27, s93, 0
	s_add_u32 s28, s92, 0x1db3f500
	s_addc_u32 s29, s93, 0
	s_add_u32 s30, s92, 0x1db3f600
	s_addc_u32 s31, s93, 0
	s_add_u32 s36, s92, 0x1db3f700
	s_addc_u32 s37, s93, 0
	s_add_u32 s38, s92, 0x1db3f800
	s_addc_u32 s39, s93, 0
	s_add_u32 s40, s92, 0x1db3f900
	s_addc_u32 s41, s93, 0
	s_add_u32 s42, s92, 0x1db3fa00
	s_addc_u32 s43, s93, 0
	s_add_u32 s44, s92, 0x1db3fb00
	s_addc_u32 s45, s93, 0
	s_mov_b32 s14, 1
	v_mov_b32_e32 v16, 0
	s_branch .LBB0_1115
